# code placement: one 4-byte s_nop at the up-projection phase entry (the up- and down-projection K-loop heads return to the byte phase they have in the baseline)
# baseline (speedup 1.0000x reference)
.LBB0_568:
	s_andn2_b64 vcc, exec, s[4:5]
	s_cbranch_vccnz .LBB0_597
	s_waitcnt lgkmcnt(0)
	s_nop 0
	s_lshl_b32 s7, s60, 8
	v_add_u32_e32 v0, s7, v9
	v_lshlrev_b32_e32 v0, 6, v0
	s_add_u32 s10, s70, 0x1b00000
	s_addc_u32 s11, s71, 0
	v_cmp_gt_u32_e32 vcc, 0x100, v9
	s_and_saveexec_b64 s[14:15], vcc
	s_cbranch_execz .Lssq_tab_done
	global_load_dwordx4 v[12:15], v0, s[10:11]
	global_load_dwordx4 v[16:19], v0, s[10:11] offset:16
	global_load_dwordx4 v[20:23], v0, s[10:11] offset:32
	global_load_dwordx4 v[24:27], v0, s[10:11] offset:48
	v_lshlrev_b32_e32 v1, 2, v9
	v_add_u32_e32 v1, 0x22000, v1
	s_waitcnt vmcnt(0)
	v_add_f32_e32 v12, v13, v12
	v_add_f32_e32 v14, v14, v15
	v_add_f32_e32 v16, v17, v16
	v_add_f32_e32 v18, v18, v19
	v_add_f32_e32 v20, v21, v20
	v_add_f32_e32 v22, v22, v23
	v_add_f32_e32 v24, v25, v24
	v_add_f32_e32 v26, v26, v27
	v_add_f32_e32 v12, v12, v14
	v_add_f32_e32 v16, v16, v18
	v_add_f32_e32 v20, v20, v22
	v_add_f32_e32 v24, v24, v26
	v_add_f32_e32 v12, v12, v16
	v_add_f32_e32 v20, v20, v24
	v_add_f32_e32 v12, v12, v20
	ds_write_b32 v1, v12
